# cmpgemm_direct: w_cmp1 B fragments staged with row-contiguous loads (8 cache lines per wave-instruction instead of 64), scattered into the MFMA fragment order on the LDS write
# baseline (speedup 1.0000x reference)
.LBB0_382:
	s_or_b64 exec, exec, s[0:1]
	s_cmpk_lt_i32 s2, 0x100
	s_mov_b64 s[4:5], s[92:93]
	v_mov_b32_e32 v2, v0
	v_readlane_b32 s0, v254, 9
	s_cselect_b64 s[42:43], -1, 0
	s_cmpk_gt_i32 s2, 0xff
	s_waitcnt lgkmcnt(0)
	s_barrier
	s_cbranch_scc1 .LBB0_387
	s_load_dwordx2 s[6:7], s[4:5], 0x30
	s_load_dwordx2 s[0:1], s[4:5], 0x40
	s_load_dwordx2 s[8:9], s[4:5], 0xd0
	v_ashrrev_i32_e32 v1, 6, v2
	v_and_b32_e32 v194, 31, v2
	v_and_b32_e32 v3, 63, v2
	v_bfe_u32 v8, v2, 5, 1
	v_lshlrev_b32_e32 v2, 16, v2
	v_lshl_or_b32 v4, v1, 5, v194
	v_and_b32_e32 v196, 0x70000, v2
	v_mov_b32_e32 v197, 0
	v_ashrrev_i32_e32 v5, 31, v4
	s_waitcnt lgkmcnt(0)
	v_lshl_add_u64 v[198:199], s[6:7], 0, v[196:197]
	v_lshlrev_b64 v[4:5], 12, v[4:5]
	v_lshlrev_b32_e32 v196, 4, v8
	v_lshl_add_u64 v[6:7], s[8:9], 0, v[4:5]
	v_lshrrev_b32_e32 v244, 3, v0
	v_and_b32_e32 v245, 7, v0
	v_lshlrev_b32_e32 v246, 12, v244
	v_lshl_or_b32 v246, v245, 4, v246
	v_mov_b32_e32 v247, 0
	v_lshl_add_u64 v[248:249], s[8:9], 0, v[246:247]
	v_bfe_u32 v250, v0, 1, 2
	v_lshlrev_b32_e32 v250, 13, v250
	v_lshrrev_b32_e32 v244, 8, v0
	v_lshl_or_b32 v250, v244, 10, v250
	v_bfe_u32 v244, v0, 3, 5
	v_lshl_or_b32 v250, v244, 4, v250
	v_and_b32_e32 v244, 1, v0
	v_lshl_or_b32 v250, v244, 9, v250
	s_mov_b64 s[100:101], 0x40000
	v_or_b32_e32 v4, v4, v196
	v_lshlrev_b32_e32 v2, 3, v8
	v_lshl_add_u64 v[6:7], v[6:7], 0, v[196:197]
	s_mov_b64 s[4:5], 0xc600000
	s_add_u32 s3, s8, 0x6fa0d000
	v_lshlrev_b32_e32 v202, 12, v8
	v_lshl_add_u64 v[4:5], s[8:9], 0, v[4:5]
	s_mov_b64 s[6:7], 0xc6000c0
	v_lshl_add_u64 v[200:201], v[6:7], 0, s[4:5]
	v_lshl_add_u64 v[248:249], v[248:249], 0, s[4:5]
	s_mov_b32 s5, 0
	v_lshl_add_u32 v195, v3, 4, 0
	s_addc_u32 s26, s9, 0
	v_mov_b32_e32 v203, v197
	v_or_b32_e32 v204, 0x2000, v202
	v_mov_b32_e32 v205, v197
	v_or_b32_e32 v206, 0x2400, v202
	v_mov_b32_e32 v207, v197
	v_or_b32_e32 v208, 0x2800, v202
	v_mov_b32_e32 v209, v197
	v_or_b32_e32 v210, 0x2c00, v202
	v_mov_b32_e32 v211, v197
	v_or_b32_e32 v212, 0x4000, v202
	v_mov_b32_e32 v213, v197
	v_or_b32_e32 v214, 0x4400, v202
	v_mov_b32_e32 v215, v197
	v_or_b32_e32 v216, 0x4800, v202
	v_mov_b32_e32 v217, v197
	v_or_b32_e32 v218, 0x4c00, v202
	v_mov_b32_e32 v219, v197
	v_or_b32_e32 v220, 0x6000, v202
	v_mov_b32_e32 v221, v197
	v_or_b32_e32 v222, 0x6400, v202
	v_mov_b32_e32 v223, v197
	v_or_b32_e32 v224, 0x6800, v202
	v_mov_b32_e32 v225, v197
	v_or_b32_e32 v226, 0x6c00, v202
	v_mov_b32_e32 v227, v197
	v_lshl_add_u64 v[228:229], v[4:5], 0, s[6:7]
	v_lshlrev_b32_e32 v230, 2, v2
	s_mov_b64 s[6:7], 0x80
	s_mov_b64 s[8:9], 0x100
	s_mov_b64 s[10:11], 0x180
	s_mov_b64 s[12:13], 0x200
	s_mov_b64 s[14:15], 0x280
	s_mov_b64 s[16:17], 0x300
	s_mov_b64 s[18:19], 0x380
	v_mov_b32_e32 v231, v197
	s_mov_b32 s27, s2
.LBB0_384:
	v_readfirstlane_b32 s4, v1
	s_lshl_b32 s20, s27, 8
	s_and_b32 s20, s20, 0x7f00
	s_lshl_b32 s21, s4, 5
	s_add_i32 s20, s21, s20
	s_and_b32 s21, s20, 0x1e0
	v_or_b32_e32 v2, s21, v194
	s_ashr_i32 s21, s20, 4
	s_andn2_b32 s21, s21, 63
	v_lshrrev_b32_e32 v2, 3, v2
	s_ashr_i32 s22, s27, 7
	v_or_b32_e32 v2, s21, v2
	v_ashrrev_i32_e32 v3, 31, v2
	s_ashr_i32 s23, s22, 31
	v_lshl_add_u64 v[2:3], v[2:3], 2, s[0:1]
	s_lshl_b64 s[24:25], s[22:23], 20
	global_load_dword v62, v[2:3], off
	v_lshl_add_u64 v[236:237], v[248:249], 0, s[24:25]
	v_lshl_add_u64 v[238:239], v[236:237], 0, s[100:101]
	v_lshl_add_u64 v[240:241], v[238:239], 0, s[100:101]
	v_lshl_add_u64 v[242:243], v[240:241], 0, s[100:101]
	s_barrier
	global_load_dwordx4 v[46:49], v[236:237], off
	global_load_dwordx4 v[50:53], v[238:239], off
	global_load_dwordx4 v[54:57], v[240:241], off
	global_load_dwordx4 v[58:61], v[242:243], off
	v_lshl_add_u64 v[236:237], v[236:237], 0, s[6:7]
	v_lshl_add_u64 v[238:239], v[238:239], 0, s[6:7]
	v_lshl_add_u64 v[240:241], v[240:241], 0, s[6:7]
	v_lshl_add_u64 v[242:243], v[242:243], 0, s[6:7]
	v_mov_b32_e32 v196, v250
	s_lshl_b32 s30, s22, 8
	s_ashr_i32 s31, s30, 31
	s_and_b32 s4, s20, 0x200
	s_mov_b32 s21, 64
	s_movk_i32 s28, 0x800
	s_mov_b32 s29, s5
	v_mov_b32_e32 v2, 0
	v_mov_b32_e32 v3, v197
	v_mov_b32_e32 v4, v197
	v_mov_b32_e32 v5, v197
	v_mov_b32_e32 v6, v197
	v_mov_b32_e32 v7, v197
	v_mov_b32_e32 v8, v197
	v_mov_b32_e32 v9, v197
	v_mov_b32_e32 v10, v197
	v_mov_b32_e32 v11, v197
	v_mov_b32_e32 v12, v197
	v_mov_b32_e32 v13, v197
	v_mov_b32_e32 v14, v197
	v_mov_b32_e32 v15, v197
	v_mov_b32_e32 v16, v197
	v_mov_b32_e32 v17, v197
	v_mov_b32_e32 v18, 0
	v_mov_b32_e32 v19, v197
	v_mov_b32_e32 v20, v197
	v_mov_b32_e32 v21, v197
	v_mov_b32_e32 v22, v197
	v_mov_b32_e32 v23, v197
	v_mov_b32_e32 v24, v197
	v_mov_b32_e32 v25, v197
	v_mov_b32_e32 v26, v197
	v_mov_b32_e32 v27, v197
	v_mov_b32_e32 v28, v197
	v_mov_b32_e32 v29, v197
	v_mov_b32_e32 v30, v197
	v_mov_b32_e32 v31, v197
	v_mov_b32_e32 v32, v197
	v_mov_b32_e32 v33, v197
	v_mov_b32_e32 v34, 0
	v_mov_b32_e32 v35, v197
	v_mov_b32_e32 v36, v197
	v_mov_b32_e32 v37, v197
	v_mov_b32_e32 v38, v197
	v_mov_b32_e32 v39, v197
	v_mov_b32_e32 v40, v197
	v_mov_b32_e32 v41, v197
	v_mov_b32_e32 v42, v197
	v_mov_b32_e32 v43, v197
	v_mov_b32_e32 v44, v197
	v_mov_b32_e32 v45, v197
	v_mov_b32_e32 v64, v197
	v_mov_b32_e32 v65, v197
	v_mov_b32_e32 v66, 0
	v_mov_b32_e32 v67, v197
	v_mov_b32_e32 v68, v197
	v_mov_b32_e32 v69, v197
	v_mov_b32_e32 v70, v197
	v_mov_b32_e32 v71, v197
	v_mov_b32_e32 v72, v197
	v_mov_b32_e32 v73, v197
	v_mov_b32_e32 v74, v197
	v_mov_b32_e32 v75, v197
	v_mov_b32_e32 v76, v197
	v_mov_b32_e32 v77, v197
	v_mov_b32_e32 v78, v197
	v_mov_b32_e32 v79, v197
	s_waitcnt vmcnt(3)
	ds_write_b128 v196, v[46:49]
	s_waitcnt vmcnt(2)
	ds_write_b128 v196, v[50:53] offset:2048
	s_waitcnt vmcnt(1)
	ds_write_b128 v196, v[54:57] offset:4096
	s_waitcnt vmcnt(0)
	ds_write_b128 v196, v[58:61] offset:6144
	v_ashrrev_i32_e32 v63, 31, v62
	v_lshlrev_b64 v[46:47], 19, v[62:63]
	v_lshl_add_u64 v[46:47], v[198:199], 0, v[46:47]
	v_lshl_add_u64 v[46:47], s[30:31], 2, v[46:47]
	v_lshl_add_u64 v[46:47], v[46:47], 0, s[4:5]
	v_lshl_add_u64 v[234:235], v[46:47], 0, v[230:231]
	global_load_dwordx4 v[162:165], v[234:235], off
	global_load_dwordx4 v[166:169], v[234:235], off offset:16
	global_load_dwordx4 v[154:157], v[234:235], off offset:64
	global_load_dwordx4 v[158:161], v[234:235], off offset:80
	global_load_dwordx4 v[142:145], v[234:235], off offset:128
	global_load_dwordx4 v[150:153], v[234:235], off offset:144
	global_load_dwordx4 v[130:133], v[234:235], off offset:192
	global_load_dwordx4 v[134:137], v[234:235], off offset:208
	s_waitcnt lgkmcnt(0)
	s_barrier
	v_mov_b32_e32 v46, v197
	v_mov_b32_e32 v47, v197
	v_mov_b32_e32 v48, v197
	v_mov_b32_e32 v49, v197
	v_mov_b32_e32 v50, 0
	v_mov_b32_e32 v51, v197
	v_mov_b32_e32 v52, v197
	v_mov_b32_e32 v53, v197
	v_mov_b32_e32 v54, v197
	v_mov_b32_e32 v55, v197
	v_mov_b32_e32 v56, v197
	v_mov_b32_e32 v57, v197
	v_mov_b32_e32 v58, v197
	v_mov_b32_e32 v59, v197
	v_mov_b32_e32 v60, v197
	v_mov_b32_e32 v61, v197
	v_mov_b32_e32 v62, v197
	v_mov_b32_e32 v63, v197
	v_mov_b32_e32 v80, v197
	v_mov_b32_e32 v81, v197
	v_mov_b32_e32 v82, 0
	v_mov_b32_e32 v83, v197
	v_mov_b32_e32 v84, v197
	v_mov_b32_e32 v85, v197
	v_mov_b32_e32 v86, v197
	v_mov_b32_e32 v87, v197
	v_mov_b32_e32 v88, v197
	v_mov_b32_e32 v89, v197
	v_mov_b32_e32 v90, v197
	v_mov_b32_e32 v91, v197
	v_mov_b32_e32 v92, v197
	v_mov_b32_e32 v93, v197
	v_mov_b32_e32 v94, v197
	v_mov_b32_e32 v95, v197
	v_mov_b32_e32 v96, v197
	v_mov_b32_e32 v97, v197
	v_mov_b32_e32 v98, 0
	v_mov_b32_e32 v99, v197
	v_mov_b32_e32 v100, v197
	v_mov_b32_e32 v101, v197
	v_mov_b32_e32 v102, v197
	v_mov_b32_e32 v103, v197
	v_mov_b32_e32 v104, v197
	v_mov_b32_e32 v105, v197
	v_mov_b32_e32 v106, v197
	v_mov_b32_e32 v107, v197
	v_mov_b32_e32 v108, v197
	v_mov_b32_e32 v109, v197
	v_mov_b32_e32 v110, v197
	v_mov_b32_e32 v111, v197
	v_mov_b32_e32 v112, v197
	v_mov_b32_e32 v113, v197
	v_mov_b32_e32 v114, 0
	v_mov_b32_e32 v115, v197
	v_mov_b32_e32 v116, v197
	v_mov_b32_e32 v117, v197
	v_mov_b32_e32 v118, v197
	v_mov_b32_e32 v119, v197
	v_mov_b32_e32 v120, v197
	v_mov_b32_e32 v121, v197
	v_mov_b32_e32 v122, v197
	v_mov_b32_e32 v123, v197
	v_mov_b32_e32 v124, v197
	v_mov_b32_e32 v125, v197
	v_mov_b32_e32 v126, v197
	v_mov_b32_e32 v127, v197
	v_mov_b32_e32 v128, v197
	v_mov_b32_e32 v129, v197
.LBB0_385:
	s_and_b32 s4, s29, 0x8000
	s_waitcnt vmcnt(6)
	v_cvt_pk_bf16_f32 v141, v168, v169
	v_add_u32_e32 v168, s4, v195
	v_cvt_pk_bf16_f32 v138, v162, v163
	v_cvt_pk_bf16_f32 v139, v164, v165
	v_cvt_pk_bf16_f32 v140, v166, v167
	ds_read_b128 v[146:149], v168
	ds_read_b128 v[162:165], v168 offset:1024
	s_waitcnt lgkmcnt(1)
	v_mfma_f32_32x32x16_bf16 v[114:129], v[138:141], v[146:149], v[114:129]
	s_waitcnt vmcnt(1)
	v_cvt_pk_bf16_f32 v130, v130, v131
	v_cvt_pk_bf16_f32 v131, v132, v133
	s_waitcnt vmcnt(0)
	v_cvt_pk_bf16_f32 v132, v134, v135
	v_cvt_pk_bf16_f32 v133, v136, v137
	s_and_b32 s4, s28, 0x1f000
	s_and_b32 s24, s21, 64
	s_add_i32 s29, s29, 0x8000
	s_waitcnt lgkmcnt(0)
	v_mfma_f32_32x32x16_bf16 v[98:113], v[138:141], v[162:165], v[98:113]
	ds_read_b128 v[146:149], v168 offset:2048
	ds_read_b128 v[162:165], v168 offset:3072
	s_addk_i32 s28, 0x800
	s_add_i32 s21, s21, 64
	s_waitcnt lgkmcnt(1)
	v_mfma_f32_32x32x16_bf16 v[82:97], v[138:141], v[146:149], v[82:97]
	s_waitcnt lgkmcnt(0)
	v_mfma_f32_32x32x16_bf16 v[66:81], v[138:141], v[162:165], v[66:81]
	ds_read_b128 v[146:149], v168 offset:4096
	ds_read_b128 v[162:165], v168 offset:5120
	s_waitcnt lgkmcnt(1)
	v_mfma_f32_32x32x16_bf16 v[50:65], v[138:141], v[146:149], v[50:65]
	s_waitcnt lgkmcnt(0)
	v_mfma_f32_32x32x16_bf16 v[34:49], v[138:141], v[162:165], v[34:49]
	ds_read_b128 v[146:149], v168 offset:6144
	ds_read_b128 v[162:165], v168 offset:7168
	s_waitcnt lgkmcnt(1)
	v_mfma_f32_32x32x16_bf16 v[18:33], v[138:141], v[146:149], v[18:33]
	v_cvt_pk_bf16_f32 v146, v154, v155
	v_cvt_pk_bf16_f32 v147, v156, v157
	v_cvt_pk_bf16_f32 v148, v158, v159
	v_cvt_pk_bf16_f32 v149, v160, v161
	s_waitcnt lgkmcnt(0)
	v_mfma_f32_32x32x16_bf16 v[2:17], v[138:141], v[162:165], v[2:17]
	ds_read_b128 v[138:141], v168 offset:8192
	ds_read_b128 v[154:157], v168 offset:9216
	s_waitcnt lgkmcnt(1)
	v_mfma_f32_32x32x16_bf16 v[114:129], v[146:149], v[138:141], v[114:129]
	s_waitcnt lgkmcnt(0)
	v_mfma_f32_32x32x16_bf16 v[98:113], v[146:149], v[154:157], v[98:113]
	ds_read_b128 v[138:141], v168 offset:10240
	ds_read_b128 v[154:157], v168 offset:11264
	s_waitcnt lgkmcnt(1)
	v_mfma_f32_32x32x16_bf16 v[82:97], v[146:149], v[138:141], v[82:97]
	s_waitcnt lgkmcnt(0)
	v_mfma_f32_32x32x16_bf16 v[66:81], v[146:149], v[154:157], v[66:81]
	ds_read_b128 v[138:141], v168 offset:12288
	ds_read_b128 v[154:157], v168 offset:13312
	s_waitcnt lgkmcnt(1)
	v_mfma_f32_32x32x16_bf16 v[50:65], v[146:149], v[138:141], v[50:65]
	s_waitcnt lgkmcnt(0)
	v_mfma_f32_32x32x16_bf16 v[34:49], v[146:149], v[154:157], v[34:49]
	ds_read_b128 v[138:141], v168 offset:14336
	ds_read_b128 v[154:157], v168 offset:15360
	s_waitcnt lgkmcnt(1)
	v_mfma_f32_32x32x16_bf16 v[18:33], v[146:149], v[138:141], v[18:33]
	v_cvt_pk_bf16_f32 v138, v142, v143
	v_cvt_pk_bf16_f32 v139, v144, v145
	v_cvt_pk_bf16_f32 v140, v150, v151
	v_cvt_pk_bf16_f32 v141, v152, v153
	s_waitcnt lgkmcnt(0)
	v_mfma_f32_32x32x16_bf16 v[2:17], v[146:149], v[154:157], v[2:17]
	ds_read_b128 v[142:145], v168 offset:16384
	ds_read_b128 v[146:149], v168 offset:17408
	s_waitcnt lgkmcnt(1)
	v_mfma_f32_32x32x16_bf16 v[114:129], v[138:141], v[142:145], v[114:129]
	s_waitcnt lgkmcnt(0)
	v_mfma_f32_32x32x16_bf16 v[98:113], v[138:141], v[146:149], v[98:113]
	ds_read_b128 v[142:145], v168 offset:18432
	ds_read_b128 v[146:149], v168 offset:19456
	s_waitcnt lgkmcnt(1)
	v_mfma_f32_32x32x16_bf16 v[82:97], v[138:141], v[142:145], v[82:97]
	s_waitcnt lgkmcnt(0)
	v_mfma_f32_32x32x16_bf16 v[66:81], v[138:141], v[146:149], v[66:81]
	ds_read_b128 v[142:145], v168 offset:20480
	ds_read_b128 v[146:149], v168 offset:21504
	s_waitcnt lgkmcnt(1)
	v_mfma_f32_32x32x16_bf16 v[50:65], v[138:141], v[142:145], v[50:65]
	s_waitcnt lgkmcnt(0)
	v_mfma_f32_32x32x16_bf16 v[34:49], v[138:141], v[146:149], v[34:49]
	ds_read_b128 v[142:145], v168 offset:22528
	ds_read_b128 v[146:149], v168 offset:23552
	s_waitcnt lgkmcnt(1)
	v_mfma_f32_32x32x16_bf16 v[18:33], v[138:141], v[142:145], v[18:33]
	s_waitcnt lgkmcnt(0)
	v_mfma_f32_32x32x16_bf16 v[2:17], v[138:141], v[146:149], v[2:17]
	ds_read_b128 v[134:137], v168 offset:24576
	ds_read_b128 v[138:141], v168 offset:25600
	v_lshl_add_u64 v[146:147], v[234:235], 0, s[4:5]
	s_lshl_b32 s4, s24, 2
	v_lshl_add_u64 v[166:167], v[146:147], 0, s[4:5]
	s_and_b32 s4, s29, 0x8000
	s_cmp_lg_u32 s29, 0xf8000
	s_waitcnt lgkmcnt(1)
	v_mfma_f32_32x32x16_bf16 v[114:129], v[130:133], v[134:137], v[114:129]
	global_load_dwordx4 v[134:137], v[236:237], off
	global_load_dwordx4 v[142:145], v[238:239], off
	global_load_dwordx4 v[150:153], v[240:241], off
	global_load_dwordx4 v[154:157], v[242:243], off
	v_lshl_add_u64 v[236:237], v[236:237], 0, s[6:7]
	v_lshl_add_u64 v[238:239], v[238:239], 0, s[6:7]
	v_lshl_add_u64 v[240:241], v[240:241], 0, s[6:7]
	v_lshl_add_u64 v[242:243], v[242:243], 0, s[6:7]
	s_waitcnt lgkmcnt(0)
	v_mfma_f32_32x32x16_bf16 v[98:113], v[130:133], v[138:141], v[98:113]
	ds_read_b128 v[138:141], v168 offset:26624
	ds_read_b128 v[146:149], v168 offset:27648
	ds_read_b128 v[158:161], v168 offset:28672
	ds_read_b128 v[162:165], v168 offset:29696
	global_load_dwordx4 v[190:193], v[166:167], off
	global_load_dwordx4 v[186:189], v[166:167], off offset:16
	global_load_dwordx4 v[182:185], v[166:167], off offset:64
	global_load_dwordx4 v[178:181], v[166:167], off offset:80
	global_load_dwordx4 v[174:177], v[166:167], off offset:128
	s_waitcnt vmcnt(3)
	v_mov_b32_e32 v169, v189
	s_waitcnt lgkmcnt(3)
	v_mfma_f32_32x32x16_bf16 v[82:97], v[130:133], v[138:141], v[82:97]
	s_waitcnt lgkmcnt(2)
	v_mfma_f32_32x32x16_bf16 v[66:81], v[130:133], v[146:149], v[66:81]
	global_load_dwordx4 v[170:173], v[166:167], off offset:144
	global_load_dwordx4 v[146:149], v[166:167], off offset:192
	global_load_dwordx4 v[138:141], v[166:167], off offset:208
	v_mov_b32_e32 v166, v186
	v_mov_b32_e32 v167, v187
	s_waitcnt lgkmcnt(1)
	v_mfma_f32_32x32x16_bf16 v[50:65], v[130:133], v[158:161], v[50:65]
	s_waitcnt lgkmcnt(0)
	v_mfma_f32_32x32x16_bf16 v[34:49], v[130:133], v[162:165], v[34:49]
	ds_read_b128 v[158:161], v168 offset:30720
	ds_read_b128 v[162:165], v168 offset:31744
	v_mov_b32_e32 v168, v188
	s_waitcnt lgkmcnt(1)
	v_mfma_f32_32x32x16_bf16 v[18:33], v[130:133], v[158:161], v[18:33]
	v_add_u32_e32 v158, s4, v196
	ds_write_b128 v158, v[134:137]
	ds_write_b128 v158, v[142:145] offset:2048
	ds_write_b128 v158, v[150:153] offset:4096
	ds_write_b128 v158, v[154:157] offset:6144
	s_waitcnt lgkmcnt(0)
	s_barrier
	s_waitcnt vmcnt(5)
	v_mov_b32_e32 v154, v182
	v_mov_b32_e32 v155, v183
	v_mov_b32_e32 v156, v184
	v_mov_b32_e32 v157, v185
	s_waitcnt lgkmcnt(4)
	v_mfma_f32_32x32x16_bf16 v[2:17], v[130:133], v[162:165], v[2:17]
	v_mov_b32_e32 v162, v190
	v_mov_b32_e32 v163, v191
	v_mov_b32_e32 v164, v192
	v_mov_b32_e32 v165, v193
	s_waitcnt vmcnt(4)
	v_mov_b32_e32 v158, v178
	v_mov_b32_e32 v159, v179
	v_mov_b32_e32 v160, v180
	v_mov_b32_e32 v161, v181
	s_waitcnt vmcnt(3)
	v_mov_b32_e32 v142, v174
	v_mov_b32_e32 v143, v175
	v_mov_b32_e32 v144, v176
	v_mov_b32_e32 v145, v177
	s_waitcnt vmcnt(2)
	v_mov_b32_e32 v150, v170
	v_mov_b32_e32 v151, v171
	v_mov_b32_e32 v152, v172
	v_mov_b32_e32 v153, v173
	s_waitcnt vmcnt(1)
	v_mov_b32_e32 v130, v146
	v_mov_b32_e32 v131, v147
	v_mov_b32_e32 v132, v148
	v_mov_b32_e32 v133, v149
	s_waitcnt vmcnt(0)
	v_mov_b32_e32 v134, v138
	v_mov_b32_e32 v135, v139
	v_mov_b32_e32 v136, v140
	v_mov_b32_e32 v137, v141
	s_cbranch_scc1 .LBB0_385
	v_cvt_pk_bf16_f32 v130, v190, v191
	v_cvt_pk_bf16_f32 v131, v192, v193
	v_cvt_pk_bf16_f32 v132, v186, v187
	v_cvt_pk_bf16_f32 v133, v188, v189
	ds_read_b128 v[134:137], v195 offset:32768
	s_lshl_b64 s[22:23], s[22:23], 25
	s_waitcnt lgkmcnt(0)
	v_mfma_f32_32x32x16_bf16 v[114:129], v[130:133], v[134:137], v[114:129]
	ds_read_b128 v[134:137], v195 offset:33792
	s_add_u32 s4, s3, s22
	s_addc_u32 s22, s26, s23
	s_ashr_i32 s21, s20, 31
	s_lshl_b64 s[20:21], s[20:21], 10
	s_add_u32 s20, s4, s20
	s_addc_u32 s21, s22, s21
	s_waitcnt lgkmcnt(0)
	v_mfma_f32_32x32x16_bf16 v[98:113], v[130:133], v[134:137], v[98:113]
	ds_read_b128 v[134:137], v195 offset:34816
	v_lshlrev_b32_e32 v196, 2, v194
	s_add_i32 s27, s27, s33
	s_cmpk_gt_i32 s27, 0xff
	s_waitcnt lgkmcnt(0)
	v_mfma_f32_32x32x16_bf16 v[82:97], v[130:133], v[134:137], v[82:97]
	ds_read_b128 v[134:137], v195 offset:35840
	s_waitcnt lgkmcnt(0)
	v_mfma_f32_32x32x16_bf16 v[66:81], v[130:133], v[134:137], v[66:81]
	ds_read_b128 v[134:137], v195 offset:36864
	s_waitcnt lgkmcnt(0)
	v_mfma_f32_32x32x16_bf16 v[50:65], v[130:133], v[134:137], v[50:65]
	ds_read_b128 v[134:137], v195 offset:37888
	s_waitcnt lgkmcnt(0)
	v_mfma_f32_32x32x16_bf16 v[34:49], v[130:133], v[134:137], v[34:49]
	ds_read_b128 v[134:137], v195 offset:38912
	s_waitcnt lgkmcnt(0)
	v_mfma_f32_32x32x16_bf16 v[18:33], v[130:133], v[134:137], v[18:33]
	ds_read_b128 v[134:137], v195 offset:39936
	s_waitcnt lgkmcnt(0)
	v_mfma_f32_32x32x16_bf16 v[2:17], v[130:133], v[134:137], v[2:17]
	v_cvt_pk_bf16_f32 v130, v182, v183
	v_cvt_pk_bf16_f32 v131, v184, v185
	v_cvt_pk_bf16_f32 v132, v178, v179
	v_cvt_pk_bf16_f32 v133, v180, v181
	ds_read_b128 v[134:137], v195 offset:40960
	s_waitcnt lgkmcnt(0)
	v_mfma_f32_32x32x16_bf16 v[114:129], v[130:133], v[134:137], v[114:129]
	ds_read_b128 v[134:137], v195 offset:41984
	s_waitcnt lgkmcnt(0)
	v_mfma_f32_32x32x16_bf16 v[98:113], v[130:133], v[134:137], v[98:113]
	ds_read_b128 v[134:137], v195 offset:43008
	s_waitcnt lgkmcnt(0)
	v_mfma_f32_32x32x16_bf16 v[82:97], v[130:133], v[134:137], v[82:97]
	ds_read_b128 v[134:137], v195 offset:44032
	s_waitcnt lgkmcnt(0)
	v_mfma_f32_32x32x16_bf16 v[66:81], v[130:133], v[134:137], v[66:81]
	ds_read_b128 v[134:137], v195 offset:45056
	s_waitcnt lgkmcnt(0)
	v_mfma_f32_32x32x16_bf16 v[50:65], v[130:133], v[134:137], v[50:65]
	ds_read_b128 v[134:137], v195 offset:46080
	s_waitcnt lgkmcnt(0)
	v_mfma_f32_32x32x16_bf16 v[34:49], v[130:133], v[134:137], v[34:49]
	ds_read_b128 v[134:137], v195 offset:47104
	s_waitcnt lgkmcnt(0)
	v_mfma_f32_32x32x16_bf16 v[18:33], v[130:133], v[134:137], v[18:33]
	ds_read_b128 v[134:137], v195 offset:48128
	s_waitcnt lgkmcnt(0)
	v_mfma_f32_32x32x16_bf16 v[2:17], v[130:133], v[134:137], v[2:17]
	v_cvt_pk_bf16_f32 v130, v174, v175
	v_cvt_pk_bf16_f32 v131, v176, v177
	v_cvt_pk_bf16_f32 v132, v170, v171
	v_cvt_pk_bf16_f32 v133, v172, v173
	ds_read_b128 v[134:137], v195 offset:49152
	s_waitcnt lgkmcnt(0)
	v_mfma_f32_32x32x16_bf16 v[114:129], v[130:133], v[134:137], v[114:129]
	ds_read_b128 v[134:137], v195 offset:50176
	s_waitcnt lgkmcnt(0)
	v_mfma_f32_32x32x16_bf16 v[98:113], v[130:133], v[134:137], v[98:113]
	ds_read_b128 v[134:137], v195 offset:51200
	s_waitcnt lgkmcnt(0)
	v_mfma_f32_32x32x16_bf16 v[82:97], v[130:133], v[134:137], v[82:97]
	ds_read_b128 v[134:137], v195 offset:52224
	s_waitcnt lgkmcnt(0)
	v_mfma_f32_32x32x16_bf16 v[66:81], v[130:133], v[134:137], v[66:81]
	ds_read_b128 v[134:137], v195 offset:53248
	s_waitcnt lgkmcnt(0)
	v_mfma_f32_32x32x16_bf16 v[50:65], v[130:133], v[134:137], v[50:65]
	ds_read_b128 v[134:137], v195 offset:54272
	s_waitcnt lgkmcnt(0)
	v_mfma_f32_32x32x16_bf16 v[34:49], v[130:133], v[134:137], v[34:49]
	ds_read_b128 v[134:137], v195 offset:55296
	s_waitcnt lgkmcnt(0)
	v_mfma_f32_32x32x16_bf16 v[18:33], v[130:133], v[134:137], v[18:33]
	ds_read_b128 v[134:137], v195 offset:56320
	s_waitcnt lgkmcnt(0)
	v_mfma_f32_32x32x16_bf16 v[2:17], v[130:133], v[134:137], v[2:17]
	v_cvt_pk_bf16_f32 v130, v146, v147
	v_cvt_pk_bf16_f32 v131, v148, v149
	v_cvt_pk_bf16_f32 v132, v138, v139
	v_cvt_pk_bf16_f32 v133, v140, v141
	ds_read_b128 v[134:137], v195 offset:57344
	s_waitcnt lgkmcnt(0)
	v_mfma_f32_32x32x16_bf16 v[114:129], v[130:133], v[134:137], v[114:129]
	ds_read_b128 v[134:137], v195 offset:58368
	s_waitcnt lgkmcnt(0)
	v_mfma_f32_32x32x16_bf16 v[98:113], v[130:133], v[134:137], v[98:113]
	ds_read_b128 v[134:137], v195 offset:59392
	s_waitcnt lgkmcnt(0)
	v_mfma_f32_32x32x16_bf16 v[82:97], v[130:133], v[134:137], v[82:97]
	ds_read_b128 v[134:137], v195 offset:60416
	s_waitcnt lgkmcnt(0)
	v_mfma_f32_32x32x16_bf16 v[66:81], v[130:133], v[134:137], v[66:81]
	ds_read_b128 v[134:137], v195 offset:61440
	s_waitcnt lgkmcnt(0)
	v_mfma_f32_32x32x16_bf16 v[50:65], v[130:133], v[134:137], v[50:65]
	ds_read_b128 v[134:137], v195 offset:62464
	s_waitcnt lgkmcnt(0)
	v_mfma_f32_32x32x16_bf16 v[34:49], v[130:133], v[134:137], v[34:49]
	ds_read_b128 v[134:137], v195 offset:63488
	s_waitcnt lgkmcnt(0)
	v_mfma_f32_32x32x16_bf16 v[18:33], v[130:133], v[134:137], v[18:33]
	ds_read_b128 v[134:137], v195 offset:64512
	s_waitcnt lgkmcnt(0)
	s_barrier
	s_waitcnt lgkmcnt(0)
	v_mfma_f32_32x32x16_bf16 v[2:17], v[130:133], v[134:137], v[2:17]
	v_lshl_add_u64 v[132:133], s[20:21], 0, v[196:197]
	v_lshl_add_u64 v[130:131], v[132:133], 0, v[202:203]
	global_store_dword v[130:131], v114, off
	global_store_dword v[130:131], v115, off offset:1024
	global_store_dword v[130:131], v116, off offset:2048
	global_store_dword v[130:131], v117, off offset:3072
	v_lshl_add_u64 v[114:115], v[132:133], 0, v[204:205]
	global_store_dword v[114:115], v118, off
	v_lshl_add_u64 v[114:115], v[132:133], 0, v[206:207]
	global_store_dword v[114:115], v119, off
	v_lshl_add_u64 v[114:115], v[132:133], 0, v[208:209]
	global_store_dword v[114:115], v120, off
	v_lshl_add_u64 v[114:115], v[132:133], 0, v[210:211]
	global_store_dword v[114:115], v121, off
	v_lshl_add_u64 v[114:115], v[132:133], 0, v[212:213]
	global_store_dword v[114:115], v122, off
	v_lshl_add_u64 v[114:115], v[132:133], 0, v[214:215]
	global_store_dword v[114:115], v123, off
	v_lshl_add_u64 v[114:115], v[132:133], 0, v[216:217]
	global_store_dword v[114:115], v124, off
	v_lshl_add_u64 v[114:115], v[132:133], 0, v[218:219]
	global_store_dword v[114:115], v125, off
	v_lshl_add_u64 v[114:115], v[132:133], 0, v[220:221]
	global_store_dword v[114:115], v126, off
	v_lshl_add_u64 v[114:115], v[132:133], 0, v[222:223]
	global_store_dword v[114:115], v127, off
	v_lshl_add_u64 v[114:115], v[132:133], 0, v[224:225]
	global_store_dword v[114:115], v128, off
	v_lshl_add_u64 v[114:115], v[132:133], 0, v[226:227]
	global_store_dword v[114:115], v129, off
	v_lshl_add_u64 v[114:115], v[132:133], 0, s[6:7]
	global_store_dword v[130:131], v98, off offset:128
	global_store_dword v[130:131], v99, off offset:1152
	global_store_dword v[130:131], v100, off offset:2176
	global_store_dword v[130:131], v101, off offset:3200
	v_lshl_add_u64 v[98:99], v[114:115], 0, v[204:205]
	global_store_dword v[98:99], v102, off
	v_lshl_add_u64 v[98:99], v[114:115], 0, v[206:207]
	global_store_dword v[98:99], v103, off
	v_lshl_add_u64 v[98:99], v[114:115], 0, v[208:209]
	global_store_dword v[98:99], v104, off
	v_lshl_add_u64 v[98:99], v[114:115], 0, v[210:211]
	global_store_dword v[98:99], v105, off
	v_lshl_add_u64 v[98:99], v[114:115], 0, v[212:213]
	global_store_dword v[98:99], v106, off
	v_lshl_add_u64 v[98:99], v[114:115], 0, v[214:215]
	global_store_dword v[98:99], v107, off
	v_lshl_add_u64 v[98:99], v[114:115], 0, v[216:217]
	global_store_dword v[98:99], v108, off
	v_lshl_add_u64 v[98:99], v[114:115], 0, v[218:219]
	global_store_dword v[98:99], v109, off
	v_lshl_add_u64 v[98:99], v[114:115], 0, v[220:221]
	global_store_dword v[98:99], v110, off
	v_lshl_add_u64 v[98:99], v[114:115], 0, v[222:223]
	global_store_dword v[98:99], v111, off
	v_lshl_add_u64 v[98:99], v[114:115], 0, v[224:225]
	global_store_dword v[98:99], v112, off
	v_lshl_add_u64 v[98:99], v[114:115], 0, v[226:227]
	global_store_dword v[98:99], v113, off
	v_lshl_add_u64 v[98:99], v[132:133], 0, s[8:9]
	global_store_dword v[130:131], v82, off offset:256
	global_store_dword v[130:131], v83, off offset:1280
	global_store_dword v[130:131], v84, off offset:2304
	global_store_dword v[130:131], v85, off offset:3328
	v_lshl_add_u64 v[82:83], v[98:99], 0, v[204:205]
	global_store_dword v[82:83], v86, off
	v_lshl_add_u64 v[82:83], v[98:99], 0, v[206:207]
	global_store_dword v[82:83], v87, off
	v_lshl_add_u64 v[82:83], v[98:99], 0, v[208:209]
	global_store_dword v[82:83], v88, off
	v_lshl_add_u64 v[82:83], v[98:99], 0, v[210:211]
	global_store_dword v[82:83], v89, off
	v_lshl_add_u64 v[82:83], v[98:99], 0, v[212:213]
	global_store_dword v[82:83], v90, off
	v_lshl_add_u64 v[82:83], v[98:99], 0, v[214:215]
	global_store_dword v[82:83], v91, off
	v_lshl_add_u64 v[82:83], v[98:99], 0, v[216:217]
	global_store_dword v[82:83], v92, off
	v_lshl_add_u64 v[82:83], v[98:99], 0, v[218:219]
	global_store_dword v[82:83], v93, off
	v_lshl_add_u64 v[82:83], v[98:99], 0, v[220:221]
	global_store_dword v[82:83], v94, off
	v_lshl_add_u64 v[82:83], v[98:99], 0, v[222:223]
	global_store_dword v[82:83], v95, off
	v_lshl_add_u64 v[82:83], v[98:99], 0, v[224:225]
	global_store_dword v[82:83], v96, off
	v_lshl_add_u64 v[82:83], v[98:99], 0, v[226:227]
	global_store_dword v[82:83], v97, off
	v_lshl_add_u64 v[82:83], v[132:133], 0, s[10:11]
	global_store_dword v[130:131], v66, off offset:384
	global_store_dword v[130:131], v67, off offset:1408
	global_store_dword v[130:131], v68, off offset:2432
	global_store_dword v[130:131], v69, off offset:3456
	v_lshl_add_u64 v[66:67], v[82:83], 0, v[204:205]
	global_store_dword v[66:67], v70, off
	v_lshl_add_u64 v[66:67], v[82:83], 0, v[206:207]
	global_store_dword v[66:67], v71, off
	v_lshl_add_u64 v[66:67], v[82:83], 0, v[208:209]
	global_store_dword v[66:67], v72, off
	v_lshl_add_u64 v[66:67], v[82:83], 0, v[210:211]
	global_store_dword v[66:67], v73, off
	v_lshl_add_u64 v[66:67], v[82:83], 0, v[212:213]
	global_store_dword v[66:67], v74, off
	v_lshl_add_u64 v[66:67], v[82:83], 0, v[214:215]
	global_store_dword v[66:67], v75, off
	v_lshl_add_u64 v[66:67], v[82:83], 0, v[216:217]
	global_store_dword v[66:67], v76, off
	v_lshl_add_u64 v[66:67], v[82:83], 0, v[218:219]
	global_store_dword v[66:67], v77, off
	v_lshl_add_u64 v[66:67], v[82:83], 0, v[220:221]
	global_store_dword v[66:67], v78, off
	v_lshl_add_u64 v[66:67], v[82:83], 0, v[222:223]
	global_store_dword v[66:67], v79, off
	v_lshl_add_u64 v[66:67], v[82:83], 0, v[224:225]
	global_store_dword v[66:67], v80, off
	v_lshl_add_u64 v[66:67], v[82:83], 0, v[226:227]
	global_store_dword v[66:67], v81, off
	v_lshl_add_u64 v[66:67], v[132:133], 0, s[12:13]
	global_store_dword v[130:131], v50, off offset:512
	global_store_dword v[130:131], v51, off offset:1536
	global_store_dword v[130:131], v52, off offset:2560
	global_store_dword v[130:131], v53, off offset:3584
	v_lshl_add_u64 v[50:51], v[66:67], 0, v[204:205]
	global_store_dword v[50:51], v54, off
	v_lshl_add_u64 v[50:51], v[66:67], 0, v[206:207]
	global_store_dword v[50:51], v55, off
	v_lshl_add_u64 v[50:51], v[66:67], 0, v[208:209]
	global_store_dword v[50:51], v56, off
	v_lshl_add_u64 v[50:51], v[66:67], 0, v[210:211]
	global_store_dword v[50:51], v57, off
	v_lshl_add_u64 v[50:51], v[66:67], 0, v[212:213]
	global_store_dword v[50:51], v58, off
	v_lshl_add_u64 v[50:51], v[66:67], 0, v[214:215]
	global_store_dword v[50:51], v59, off
	v_lshl_add_u64 v[50:51], v[66:67], 0, v[216:217]
	global_store_dword v[50:51], v60, off
	v_lshl_add_u64 v[50:51], v[66:67], 0, v[218:219]
	global_store_dword v[50:51], v61, off
	v_lshl_add_u64 v[50:51], v[66:67], 0, v[220:221]
	global_store_dword v[50:51], v62, off
	v_lshl_add_u64 v[50:51], v[66:67], 0, v[222:223]
	global_store_dword v[50:51], v63, off
	v_lshl_add_u64 v[50:51], v[66:67], 0, v[224:225]
	global_store_dword v[50:51], v64, off
	v_lshl_add_u64 v[50:51], v[66:67], 0, v[226:227]
	global_store_dword v[50:51], v65, off
	v_lshl_add_u64 v[50:51], v[132:133], 0, s[14:15]
	global_store_dword v[130:131], v34, off offset:640
	global_store_dword v[130:131], v35, off offset:1664
	global_store_dword v[130:131], v36, off offset:2688
	global_store_dword v[130:131], v37, off offset:3712
	v_lshl_add_u64 v[34:35], v[50:51], 0, v[204:205]
	global_store_dword v[34:35], v38, off
	v_lshl_add_u64 v[34:35], v[50:51], 0, v[206:207]
	global_store_dword v[34:35], v39, off
	v_lshl_add_u64 v[34:35], v[50:51], 0, v[208:209]
	global_store_dword v[34:35], v40, off
	v_lshl_add_u64 v[34:35], v[50:51], 0, v[210:211]
	global_store_dword v[34:35], v41, off
	v_lshl_add_u64 v[34:35], v[50:51], 0, v[212:213]
	global_store_dword v[34:35], v42, off
	v_lshl_add_u64 v[34:35], v[50:51], 0, v[214:215]
	global_store_dword v[34:35], v43, off
	v_lshl_add_u64 v[34:35], v[50:51], 0, v[216:217]
	global_store_dword v[34:35], v44, off
	v_lshl_add_u64 v[34:35], v[50:51], 0, v[218:219]
	global_store_dword v[34:35], v45, off
	v_lshl_add_u64 v[34:35], v[50:51], 0, v[220:221]
	global_store_dword v[34:35], v46, off
	v_lshl_add_u64 v[34:35], v[50:51], 0, v[222:223]
	global_store_dword v[34:35], v47, off
	v_lshl_add_u64 v[34:35], v[50:51], 0, v[224:225]
	global_store_dword v[34:35], v48, off
	v_lshl_add_u64 v[34:35], v[50:51], 0, v[226:227]
	global_store_dword v[34:35], v49, off
	v_lshl_add_u64 v[34:35], v[132:133], 0, s[16:17]
	global_store_dword v[130:131], v18, off offset:768
	global_store_dword v[130:131], v19, off offset:1792
	global_store_dword v[130:131], v20, off offset:2816
	global_store_dword v[130:131], v21, off offset:3840
	v_lshl_add_u64 v[18:19], v[34:35], 0, v[204:205]
	global_store_dword v[18:19], v22, off
	v_lshl_add_u64 v[18:19], v[34:35], 0, v[206:207]
	global_store_dword v[18:19], v23, off
	v_lshl_add_u64 v[18:19], v[34:35], 0, v[208:209]
	global_store_dword v[18:19], v24, off
	v_lshl_add_u64 v[18:19], v[34:35], 0, v[210:211]
	global_store_dword v[18:19], v25, off
	v_lshl_add_u64 v[18:19], v[34:35], 0, v[212:213]
	global_store_dword v[18:19], v26, off
	v_lshl_add_u64 v[18:19], v[34:35], 0, v[214:215]
	global_store_dword v[18:19], v27, off
	v_lshl_add_u64 v[18:19], v[34:35], 0, v[216:217]
	global_store_dword v[18:19], v28, off
	v_lshl_add_u64 v[18:19], v[34:35], 0, v[218:219]
	global_store_dword v[18:19], v29, off
	v_lshl_add_u64 v[18:19], v[34:35], 0, v[220:221]
	global_store_dword v[18:19], v30, off
	v_lshl_add_u64 v[18:19], v[34:35], 0, v[222:223]
	global_store_dword v[18:19], v31, off
	v_lshl_add_u64 v[18:19], v[34:35], 0, v[224:225]
	global_store_dword v[18:19], v32, off
	v_lshl_add_u64 v[18:19], v[34:35], 0, v[226:227]
	global_store_dword v[18:19], v33, off
	v_lshl_add_u64 v[18:19], v[132:133], 0, s[18:19]
	global_store_dword v[130:131], v2, off offset:896
	global_store_dword v[130:131], v3, off offset:1920
	global_store_dword v[130:131], v4, off offset:2944
	global_store_dword v[130:131], v5, off offset:3968
	v_lshl_add_u64 v[2:3], v[18:19], 0, v[204:205]
	global_store_dword v[2:3], v6, off
	v_lshl_add_u64 v[2:3], v[18:19], 0, v[206:207]
	global_store_dword v[2:3], v7, off
	v_lshl_add_u64 v[2:3], v[18:19], 0, v[208:209]
	global_store_dword v[2:3], v8, off
	v_lshl_add_u64 v[2:3], v[18:19], 0, v[210:211]
	global_store_dword v[2:3], v9, off
	v_lshl_add_u64 v[2:3], v[18:19], 0, v[212:213]
	global_store_dword v[2:3], v10, off
	v_lshl_add_u64 v[2:3], v[18:19], 0, v[214:215]
	global_store_dword v[2:3], v11, off
	v_lshl_add_u64 v[2:3], v[18:19], 0, v[216:217]
	global_store_dword v[2:3], v12, off
	v_lshl_add_u64 v[2:3], v[18:19], 0, v[218:219]
	global_store_dword v[2:3], v13, off
	v_lshl_add_u64 v[2:3], v[18:19], 0, v[220:221]
	global_store_dword v[2:3], v14, off
	v_lshl_add_u64 v[2:3], v[18:19], 0, v[222:223]
	global_store_dword v[2:3], v15, off
	v_lshl_add_u64 v[2:3], v[18:19], 0, v[224:225]
	global_store_dword v[2:3], v16, off
	v_lshl_add_u64 v[2:3], v[18:19], 0, v[226:227]
	global_store_dword v[2:3], v17, off
	s_waitcnt vmcnt(63) expcnt(7) lgkmcnt(15)
	s_barrier
	s_cbranch_scc0 .LBB0_384

	.amdhsa_kernel _Z8yoco_fwd4Args
		.amdhsa_group_segment_fixed_size 0
		.amdhsa_private_segment_fixed_size 0
		.amdhsa_kernarg_size 472
		.amdhsa_user_sgpr_count 2
		.amdhsa_user_sgpr_dispatch_ptr 0
		.amdhsa_user_sgpr_queue_ptr 0
		.amdhsa_user_sgpr_kernarg_segment_ptr 1
		.amdhsa_user_sgpr_dispatch_id 0
		.amdhsa_user_sgpr_kernarg_preload_length 0
		.amdhsa_user_sgpr_kernarg_preload_offset 0
		.amdhsa_user_sgpr_private_segment_size 0
		.amdhsa_uses_dynamic_stack 0
		.amdhsa_enable_private_segment 0
		.amdhsa_system_sgpr_workgroup_id_x 1
		.amdhsa_system_sgpr_workgroup_id_y 0
		.amdhsa_system_sgpr_workgroup_id_z 0
		.amdhsa_system_sgpr_workgroup_info 0
		.amdhsa_system_vgpr_workitem_id 0
		.amdhsa_next_free_vgpr 256
		.amdhsa_next_free_sgpr 102
		.amdhsa_accum_offset 256
		.amdhsa_reserve_vcc 1
		.amdhsa_float_round_mode_32 0
		.amdhsa_float_round_mode_16_64 0
		.amdhsa_float_denorm_mode_32 3
		.amdhsa_float_denorm_mode_16_64 3
		.amdhsa_dx10_clamp 1
		.amdhsa_ieee_mode 1
		.amdhsa_fp16_overflow 0
		.amdhsa_tg_split 0
		.amdhsa_exception_fp_ieee_invalid_op 0
		.amdhsa_exception_fp_denorm_src 0
		.amdhsa_exception_fp_ieee_div_zero 0
		.amdhsa_exception_fp_ieee_overflow 0
		.amdhsa_exception_fp_ieee_underflow 0
		.amdhsa_exception_fp_ieee_inexact 0
		.amdhsa_exception_int_div_zero 0
	.end_amdhsa_kernel

.Lfunc_end0:
	.size	_Z8yoco_fwd4Args, .Lfunc_end0-_Z8yoco_fwd4Args
	.set _Z8yoco_fwd4Args.num_vgpr, 256
	.set _Z8yoco_fwd4Args.num_agpr, 0
	.set _Z8yoco_fwd4Args.numbered_sgpr, 102
	.set _Z8yoco_fwd4Args.num_named_barrier, 0
	.set _Z8yoco_fwd4Args.private_seg_size, 0
	.set _Z8yoco_fwd4Args.uses_vcc, 1
	.set _Z8yoco_fwd4Args.uses_flat_scratch, 0
	.set _Z8yoco_fwd4Args.has_dyn_sized_stack, 0
	.set _Z8yoco_fwd4Args.has_recursion, 0
	.set _Z8yoco_fwd4Args.has_indirect_call, 0

amdhsa.kernels:
  - .agpr_count:     0
    .args:
      - .offset:         0
        .size:           216
        .value_kind:     by_value
      - .offset:         216
        .size:           4
        .value_kind:     hidden_block_count_x
      - .offset:         220
        .size:           4
        .value_kind:     hidden_block_count_y
      - .offset:         224
        .size:           4
        .value_kind:     hidden_block_count_z
      - .offset:         228
        .size:           2
        .value_kind:     hidden_group_size_x
      - .offset:         230
        .size:           2
        .value_kind:     hidden_group_size_y
      - .offset:         232
        .size:           2
        .value_kind:     hidden_group_size_z
      - .offset:         234
        .size:           2
        .value_kind:     hidden_remainder_x
      - .offset:         236
        .size:           2
        .value_kind:     hidden_remainder_y
      - .offset:         238
        .size:           2
        .value_kind:     hidden_remainder_z
      - .offset:         256
        .size:           8
        .value_kind:     hidden_global_offset_x
      - .offset:         264
        .size:           8
        .value_kind:     hidden_global_offset_y
      - .offset:         272
        .size:           8
        .value_kind:     hidden_global_offset_z
      - .offset:         280
        .size:           2
        .value_kind:     hidden_grid_dims
      - .offset:         336
        .size:           4
        .value_kind:     hidden_dynamic_lds_size
    .group_segment_fixed_size: 0
    .kernarg_segment_align: 8
    .kernarg_segment_size: 472
    .language:       OpenCL C
    .language_version:
      - 2
      - 0
    .max_flat_workgroup_size: 512
    .name:           _Z8yoco_fwd4Args
    .private_segment_fixed_size: 0
    .sgpr_count:     108
    .sgpr_spill_count: 102
    .symbol:         _Z8yoco_fwd4Args.kd
    .uniform_work_group_size: 1
    .uses_dynamic_stack: false
    .vgpr_count:     256
    .vgpr_spill_count: 0
    .wavefront_size: 64
